# NORM ctx rows: split-K partial folding with 8 loads in flight; unit-start vmcnt(0) dropped in 3 GEMM loops
# speedup vs baseline: 1.0046x; 1.0046x over previous
; template <class Epi, class Sched>
; __device__ __forceinline__ void gemm_phase(PG8_LAS unsigned char* lds, const Gemm g, const Sched& S, const Epi& E) {
;     ...
;         if constexpr (!Epi::AFTER_DRAIN) { E(acc, cur, wr, wc, fr, fq); S.done(cur); }
;         if (!has_next) break;
; #pragma unroll
;         for (int a = 0; a < 2; ++a)
; #pragma unroll
;             for (int b = 0; b < 2; ++b)
; #pragma unroll
;                 for (int m = 0; m < 4; ++m)
; #pragma unroll
;                     for (int n = 0; n < 2; ++n) acc[a][b][m][n] = (f32x4){0.f, 0.f, 0.f, 0.f};
;         cur = nxt; cA = nA; cB = nB; ++ui;
.LBB0_267:
	s_add_u32 s16, s16, 0x80
	s_addc_u32 s17, s17, 0
	s_add_u32 s24, s20, 0x100
	v_mov_b32_e32 v0, 0
	s_addc_u32 s25, s21, 0
	s_mov_b32 s20, 0
	v_mov_b32_e32 v1, v0
	v_mov_b32_e32 v2, v0
	v_mov_b32_e32 v3, v0
	v_mov_b32_e32 v4, v0
	v_mov_b32_e32 v5, v0
	v_mov_b32_e32 v6, v0
	v_mov_b32_e32 v7, v0
	v_mov_b32_e32 v8, v0
	v_mov_b32_e32 v9, v0
	v_mov_b32_e32 v10, v0
	v_mov_b32_e32 v11, v0
	v_mov_b32_e32 v20, v0
	v_mov_b32_e32 v21, v0
	v_mov_b32_e32 v22, v0
	v_mov_b32_e32 v23, v0
	v_mov_b32_e32 v24, v0
	v_mov_b32_e32 v25, v0
	v_mov_b32_e32 v26, v0
	v_mov_b32_e32 v27, v0
	v_mov_b32_e32 v36, v0
	v_mov_b32_e32 v37, v0
	v_mov_b32_e32 v38, v0
	v_mov_b32_e32 v39, v0
	v_mov_b32_e32 v40, v0
	v_mov_b32_e32 v41, v0
	v_mov_b32_e32 v42, v0
	v_mov_b32_e32 v43, v0
	v_mov_b32_e32 v54, v0
	v_mov_b32_e32 v55, v0
	v_mov_b32_e32 v56, v0
	v_mov_b32_e32 v57, v0
	v_mov_b32_e32 v12, v0
	v_mov_b32_e32 v13, v0
	v_mov_b32_e32 v14, v0
	v_mov_b32_e32 v15, v0
	v_mov_b32_e32 v16, v0
	v_mov_b32_e32 v17, v0
	v_mov_b32_e32 v18, v0
	v_mov_b32_e32 v19, v0
	v_mov_b32_e32 v28, v0
	v_mov_b32_e32 v29, v0
	v_mov_b32_e32 v30, v0
	v_mov_b32_e32 v31, v0
	v_mov_b32_e32 v32, v0
	v_mov_b32_e32 v33, v0
	v_mov_b32_e32 v34, v0
	v_mov_b32_e32 v35, v0
	v_mov_b32_e32 v44, v0
	v_mov_b32_e32 v45, v0
	v_mov_b32_e32 v46, v0
	v_mov_b32_e32 v47, v0
	v_mov_b32_e32 v50, v0
	v_mov_b32_e32 v51, v0
	v_mov_b32_e32 v52, v0
	v_mov_b32_e32 v53, v0
	v_mov_b32_e32 v58, v0
	v_mov_b32_e32 v59, v0
	v_mov_b32_e32 v60, v0
	v_mov_b32_e32 v61, v0
	v_mov_b32_e32 v62, v0
	v_mov_b32_e32 v63, v0
	v_mov_b32_e32 v64, v0
	v_mov_b32_e32 v65, v0
	v_mov_b32_e32 v66, v0
	v_mov_b32_e32 v67, v0
	v_mov_b32_e32 v68, v0
	v_mov_b32_e32 v69, v0
	v_mov_b32_e32 v70, v0
	v_mov_b32_e32 v71, v0
	v_mov_b32_e32 v72, v0
	v_mov_b32_e32 v73, v0
	v_mov_b32_e32 v74, v0
	v_mov_b32_e32 v75, v0
	v_mov_b32_e32 v76, v0
	v_mov_b32_e32 v77, v0
	v_mov_b32_e32 v86, v0
	v_mov_b32_e32 v87, v0
	v_mov_b32_e32 v88, v0
	v_mov_b32_e32 v89, v0
	v_mov_b32_e32 v90, v0
	v_mov_b32_e32 v91, v0
	v_mov_b32_e32 v92, v0
	v_mov_b32_e32 v93, v0
	v_mov_b32_e32 v102, v0
	v_mov_b32_e32 v103, v0
	v_mov_b32_e32 v104, v0
	v_mov_b32_e32 v105, v0
	v_mov_b32_e32 v106, v0
	v_mov_b32_e32 v107, v0
	v_mov_b32_e32 v108, v0
	v_mov_b32_e32 v109, v0
	v_mov_b32_e32 v118, v0
	v_mov_b32_e32 v119, v0
	v_mov_b32_e32 v120, v0
	v_mov_b32_e32 v121, v0
	v_mov_b32_e32 v78, v0
	v_mov_b32_e32 v79, v0
	v_mov_b32_e32 v80, v0
	v_mov_b32_e32 v81, v0
	v_mov_b32_e32 v82, v0
	v_mov_b32_e32 v83, v0
	v_mov_b32_e32 v84, v0
	v_mov_b32_e32 v85, v0
	v_mov_b32_e32 v94, v0
	v_mov_b32_e32 v95, v0
	v_mov_b32_e32 v96, v0
	v_mov_b32_e32 v97, v0
	v_mov_b32_e32 v98, v0
	v_mov_b32_e32 v99, v0
	v_mov_b32_e32 v100, v0
	v_mov_b32_e32 v101, v0
	v_mov_b32_e32 v110, v0
	v_mov_b32_e32 v111, v0
	v_mov_b32_e32 v112, v0
	v_mov_b32_e32 v113, v0
	v_mov_b32_e32 v114, v0
	v_mov_b32_e32 v115, v0
	v_mov_b32_e32 v116, v0
	v_mov_b32_e32 v117, v0
	v_mov_b32_e32 v122, v0
	v_mov_b32_e32 v123, v0
	v_mov_b32_e32 v124, v0
	v_mov_b32_e32 v125, v0
	v_mov_b32_e32 v126, v0
	v_mov_b32_e32 v127, v0
	v_mov_b32_e32 v128, v0
	v_mov_b32_e32 v129, v0

; template <class Epi, class Sched>
; __device__ __forceinline__ void gemm_phase(PG8_LAS unsigned char* lds, const Gemm g, const Sched& S, const Epi& E) {
;     ...
;         const bool has_next = S.next(ui + 1, nxt);
;         const char* nA = has_next ? (const char*)g.A + (size_t)nxt.pm * tstepA + (size_t)nxt.kc * cstep : cA; const char* nB = has_next ? (const char*)g.Bt + (size_t)nxt.pn * tstep + (size_t)nxt.kc * cstep : cB;
;     ...
; #pragma unroll
;         for (int a = 0; a < 2; ++a)
; #pragma unroll
;             for (int b = 0; b < 2; ++b)
; #pragma unroll
;                 for (int m = 0; m < 4; ++m)
; #pragma unroll
;                     for (int n = 0; n < 2; ++n) acc[a][b][m][n] = (f32x4){0.f, 0.f, 0.f, 0.f};
;         cur = nxt; cA = nA; cB = nB; ++ui;
.LBB0_334:
	v_mov_b64_e32 v[0:1], 0x440
	s_ashr_i32 s23, s22, 31
	v_cmp_lt_i64_e32 vcc, s[16:17], v[0:1]
	s_lshl_b64 s[16:17], s[22:23], 19
	s_add_u32 s24, s28, s16
	s_addc_u32 s25, s29, s17
	s_and_b64 s[16:17], vcc, exec
	s_cselect_b32 s23, s25, s7
	s_cselect_b32 s50, s24, s6
	s_ashr_i32 s21, s20, 31
	s_lshl_b64 s[16:17], s[20:21], 19
	s_add_u32 s26, s30, s16
	s_addc_u32 s27, s31, s17
	s_and_b64 s[16:17], vcc, exec
	s_cselect_b32 s21, s27, s13
	s_cselect_b32 s51, s26, s12
	s_add_u32 s6, s6, 0x40080
	s_addc_u32 s7, s7, 0
	s_add_u32 s54, s12, 0x100
	v_mov_b32_e32 v0, 0
	s_addc_u32 s55, s13, 0
	s_mov_b32 s56, -2
	v_mov_b32_e32 v1, v0
	v_mov_b32_e32 v2, v0
	v_mov_b32_e32 v3, v0
	v_mov_b32_e32 v4, v0
	v_mov_b32_e32 v5, v0
	v_mov_b32_e32 v6, v0
	v_mov_b32_e32 v7, v0
	v_mov_b32_e32 v16, v0
	v_mov_b32_e32 v17, v0
	v_mov_b32_e32 v18, v0
	v_mov_b32_e32 v19, v0
	v_mov_b32_e32 v20, v0
	v_mov_b32_e32 v21, v0
	v_mov_b32_e32 v22, v0
	v_mov_b32_e32 v23, v0
	v_mov_b32_e32 v32, v0
	v_mov_b32_e32 v33, v0
	v_mov_b32_e32 v34, v0
	v_mov_b32_e32 v35, v0
	v_mov_b32_e32 v36, v0
	v_mov_b32_e32 v37, v0
	v_mov_b32_e32 v38, v0
	v_mov_b32_e32 v39, v0
	v_mov_b32_e32 v50, v0
	v_mov_b32_e32 v51, v0
	v_mov_b32_e32 v52, v0
	v_mov_b32_e32 v53, v0
	v_mov_b32_e32 v54, v0
	v_mov_b32_e32 v55, v0
	v_mov_b32_e32 v56, v0
	v_mov_b32_e32 v57, v0
	v_mov_b32_e32 v8, v0
	v_mov_b32_e32 v9, v0
	v_mov_b32_e32 v10, v0
	v_mov_b32_e32 v11, v0
	v_mov_b32_e32 v12, v0
	v_mov_b32_e32 v13, v0
	v_mov_b32_e32 v14, v0
	v_mov_b32_e32 v15, v0
	v_mov_b32_e32 v24, v0
	v_mov_b32_e32 v25, v0
	v_mov_b32_e32 v26, v0
	v_mov_b32_e32 v27, v0
	v_mov_b32_e32 v28, v0
	v_mov_b32_e32 v29, v0
	v_mov_b32_e32 v30, v0
	v_mov_b32_e32 v31, v0
	v_mov_b32_e32 v40, v0
	v_mov_b32_e32 v41, v0
	v_mov_b32_e32 v42, v0
	v_mov_b32_e32 v43, v0
	v_mov_b32_e32 v44, v0
	v_mov_b32_e32 v45, v0
	v_mov_b32_e32 v46, v0
	v_mov_b32_e32 v47, v0
	v_mov_b32_e32 v58, v0
	v_mov_b32_e32 v59, v0
	v_mov_b32_e32 v60, v0
	v_mov_b32_e32 v61, v0
	v_mov_b32_e32 v62, v0
	v_mov_b32_e32 v63, v0
	v_mov_b32_e32 v64, v0
	v_mov_b32_e32 v65, v0
	v_mov_b32_e32 v66, v0
	v_mov_b32_e32 v67, v0
	v_mov_b32_e32 v68, v0
	v_mov_b32_e32 v69, v0
	v_mov_b32_e32 v70, v0
	v_mov_b32_e32 v71, v0
	v_mov_b32_e32 v72, v0
	v_mov_b32_e32 v73, v0
	v_mov_b32_e32 v82, v0
	v_mov_b32_e32 v83, v0
	v_mov_b32_e32 v84, v0
	v_mov_b32_e32 v85, v0
	v_mov_b32_e32 v86, v0
	v_mov_b32_e32 v87, v0
	v_mov_b32_e32 v88, v0
	v_mov_b32_e32 v89, v0
	v_mov_b32_e32 v98, v0
	v_mov_b32_e32 v99, v0
	v_mov_b32_e32 v100, v0
	v_mov_b32_e32 v101, v0
	v_mov_b32_e32 v102, v0
	v_mov_b32_e32 v103, v0
	v_mov_b32_e32 v104, v0
	v_mov_b32_e32 v105, v0
	v_mov_b32_e32 v114, v0
	v_mov_b32_e32 v115, v0
	v_mov_b32_e32 v116, v0
	v_mov_b32_e32 v117, v0
	v_mov_b32_e32 v118, v0
	v_mov_b32_e32 v119, v0
	v_mov_b32_e32 v120, v0
	v_mov_b32_e32 v121, v0
	v_mov_b32_e32 v74, v0
	v_mov_b32_e32 v75, v0
	v_mov_b32_e32 v76, v0
	v_mov_b32_e32 v77, v0
	v_mov_b32_e32 v78, v0
	v_mov_b32_e32 v79, v0
	v_mov_b32_e32 v80, v0
	v_mov_b32_e32 v81, v0
	v_mov_b32_e32 v90, v0
	v_mov_b32_e32 v91, v0
	v_mov_b32_e32 v92, v0
	v_mov_b32_e32 v93, v0
	v_mov_b32_e32 v94, v0
	v_mov_b32_e32 v95, v0
	v_mov_b32_e32 v96, v0
	v_mov_b32_e32 v97, v0
	v_mov_b32_e32 v106, v0
	v_mov_b32_e32 v107, v0
	v_mov_b32_e32 v108, v0
	v_mov_b32_e32 v109, v0
	v_mov_b32_e32 v110, v0
	v_mov_b32_e32 v111, v0
	v_mov_b32_e32 v112, v0
	v_mov_b32_e32 v113, v0
	v_mov_b32_e32 v122, v0
	v_mov_b32_e32 v123, v0
	v_mov_b32_e32 v124, v0
	v_mov_b32_e32 v125, v0
	v_mov_b32_e32 v126, v0
	v_mov_b32_e32 v127, v0
	v_mov_b32_e32 v128, v0
	v_mov_b32_e32 v129, v0

; __device__ __forceinline__ void norm_phase(const float* xl, const float* xc, bf16_t* HN, const float* gain, const float* mods_l, int sidx, int nrows, int lane, int gw, int NGW,
;                                            float* ctxr_rw, const float* part, int npart, const float* pgate) {
;     ...
;         if (row >= ML && npart > 0) {
;             f32x4 ps[4];
; #pragma unroll
;             for (int j = 0; j < 4; ++j) ps[j] = (f32x4){0.f, 0.f, 0.f, 0.f};
;             for (int kc = 0; kc < npart; ++kc) { const f32x4* pr = (const f32x4*)(part + ((size_t)kc * MC + (row - ML)) * DM) + lane;
; #pragma unroll
;                 for (int j = 0; j < 4; ++j) ps[j] += pr[64 * j]; }
;             f32x4* wr_ = (f32x4*)(ctxr_rw + (size_t)(row - ML) * DM) + lane;
; #pragma unroll
;             for (int j = 0; j < 4; ++j) { v[j] += *(const f32x4*)(pgate + 4 * (lane + 64 * j)) * ps[j]; wr_[64 * j] = v[j]; }
;         }
.LBB0_368:
	s_cmp_lt_i32 s10, 0x8000
	s_cselect_b64 s[12:13], -1, 0
	s_or_b64 s[12:13], s[8:9], s[12:13]
	s_and_b64 vcc, exec, s[12:13]
	s_cbranch_vccnz .LBB0_351
	s_add_i32 s56, s10, 0xffff8000
	s_lshl_b64 s[12:13], s[56:57], 12
	v_mov_b32_e32 v50, 0
	v_lshl_add_u64 v[76:77], v[60:61], 0, s[12:13]
	s_mov_b64 s[16:17], 0
	v_mov_b32_e32 v51, v50
	v_mov_b32_e32 v62, v50
	v_mov_b32_e32 v63, v50
	v_mov_b32_e32 v72, v50
	v_mov_b32_e32 v73, v50
	v_mov_b32_e32 v74, v50
	v_mov_b32_e32 v75, v50
	v_mov_b32_e32 v68, v50
	v_mov_b32_e32 v69, v50
	v_mov_b32_e32 v70, v50
	v_mov_b32_e32 v71, v50
	v_mov_b32_e32 v64, v50
	v_mov_b32_e32 v65, v50
	v_mov_b32_e32 v66, v50
	v_mov_b32_e32 v67, v50
	global_load_dwordx4 v[120:123], v[58:59], off
	global_load_dwordx4 v[124:127], v[58:59], off offset:1024
	global_load_dwordx4 v[128:131], v[58:59], off offset:2048
	global_load_dwordx4 v[132:135], v[58:59], off offset:3072
.LBB0_370:
	v_lshl_add_u64 v[84:85], v[76:77], 0, s[16:17]
	s_mov_b32 s11, 0x1ca00000
	v_add_co_u32_e32 v88, vcc, s11, v84
	s_add_u32 s16, s16, 0x1000000
	s_nop 0
	v_addc_co_u32_e32 v89, vcc, 0, v85, vcc
	global_load_dwordx4 v[84:87], v[88:89], off
	global_load_dwordx4 v[90:93], v[88:89], off offset:1024
	s_mov_b64 vcc, 0x800000
	v_lshl_add_u64 v[102:103], v[88:89], 0, vcc
	global_load_dwordx4 v[94:97], v[88:89], off offset:2048
	global_load_dwordx4 v[98:101], v[88:89], off offset:3072
	global_load_dwordx4 v[104:107], v[102:103], off
	global_load_dwordx4 v[108:111], v[102:103], off offset:1024
	global_load_dwordx4 v[112:115], v[102:103], off offset:2048
	global_load_dwordx4 v[116:119], v[102:103], off offset:3072
	s_addc_u32 s17, s17, 0
	s_cmp_eq_u32 s25, s16
	s_waitcnt vmcnt(7)
	v_pk_add_f32 v[74:75], v[74:75], v[86:87]
	v_pk_add_f32 v[72:73], v[72:73], v[84:85]
	s_waitcnt vmcnt(6)
	v_pk_add_f32 v[70:71], v[70:71], v[92:93]
	v_pk_add_f32 v[68:69], v[68:69], v[90:91]
	s_waitcnt vmcnt(5)
	v_pk_add_f32 v[66:67], v[66:67], v[96:97]
	v_pk_add_f32 v[64:65], v[64:65], v[94:95]
	s_waitcnt vmcnt(4)
	v_pk_add_f32 v[62:63], v[62:63], v[100:101]
	v_pk_add_f32 v[50:51], v[50:51], v[98:99]
	s_waitcnt vmcnt(3)
	v_pk_add_f32 v[74:75], v[74:75], v[106:107]
	v_pk_add_f32 v[72:73], v[72:73], v[104:105]
	s_waitcnt vmcnt(2)
	v_pk_add_f32 v[70:71], v[70:71], v[110:111]
	v_pk_add_f32 v[68:69], v[68:69], v[108:109]
	s_waitcnt vmcnt(1)
	v_pk_add_f32 v[66:67], v[66:67], v[114:115]
	v_pk_add_f32 v[64:65], v[64:65], v[112:113]
	s_waitcnt vmcnt(0)
	v_pk_add_f32 v[62:63], v[62:63], v[118:119]
	v_pk_add_f32 v[50:51], v[50:51], v[116:117]
	s_cbranch_scc0 .LBB0_370
	v_lshl_add_u64 v[76:77], v[52:53], 0, s[12:13]
	s_waitcnt vmcnt(0)
	v_pk_fma_f32 v[46:47], v[74:75], v[122:123], v[46:47]
	v_pk_fma_f32 v[44:45], v[72:73], v[120:121], v[44:45]
	global_store_dwordx4 v[76:77], v[44:47], off
	v_pk_fma_f32 v[42:43], v[70:71], v[126:127], v[42:43]
	v_pk_fma_f32 v[40:41], v[68:69], v[124:125], v[40:41]
	global_store_dwordx4 v[76:77], v[40:43], off offset:1024
	v_pk_fma_f32 v[38:39], v[66:67], v[130:131], v[38:39]
	v_pk_fma_f32 v[36:37], v[64:65], v[128:129], v[36:37]
	global_store_dwordx4 v[76:77], v[36:39], off offset:2048
	v_pk_fma_f32 v[34:35], v[62:63], v[134:135], v[34:35]
	v_pk_fma_f32 v[32:33], v[50:51], v[132:133], v[32:33]
	global_store_dwordx4 v[76:77], v[32:35], off offset:3072
	s_branch .LBB0_351

; template <class Epi, class Sched>
; __device__ __forceinline__ void gemm_phase(PG8_LAS unsigned char* lds, const Gemm g, const Sched& S, const Epi& E) {
;     ...
;         const bool has_next = S.next(ui + 1, nxt);
;         const char* nA = has_next ? (const char*)g.A + (size_t)nxt.pm * tstepA + (size_t)nxt.kc * cstep : cA; const char* nB = has_next ? (const char*)g.Bt + (size_t)nxt.pn * tstep + (size_t)nxt.kc * cstep : cB;
;     ...
; #pragma unroll
;         for (int a = 0; a < 2; ++a)
; #pragma unroll
;             for (int b = 0; b < 2; ++b)
; #pragma unroll
;                 for (int m = 0; m < 4; ++m)
; #pragma unroll
;                     for (int n = 0; n < 2; ++n) acc[a][b][m][n] = (f32x4){0.f, 0.f, 0.f, 0.f};
;         cur = nxt; cA = nA; cB = nB; ++ui;
.LBB0_387:
	s_ashr_i32 s39, s38, 31
	s_lshl_b64 s[16:17], s[38:39], 19
	v_readlane_b32 s3, v254, 53
	s_add_u32 s94, s3, s16
	v_readlane_b32 s3, v254, 54
	s_addc_u32 s95, s3, s17
	s_and_b64 s[16:17], s[62:63], exec
	s_cselect_b32 s3, s95, s13
	s_cselect_b32 s26, s94, s12
	s_add_u32 s6, s6, 0x40080
	s_addc_u32 s7, s7, 0
	s_add_u32 s27, s12, 0x100
	v_mov_b32_e32 v0, 0
	s_addc_u32 s29, s13, 0
	s_mov_b32 s30, -2
	v_mov_b32_e32 v1, v0
	v_mov_b32_e32 v2, v0
	v_mov_b32_e32 v3, v0
	v_mov_b32_e32 v66, v0
	v_mov_b32_e32 v67, v0
	v_mov_b32_e32 v68, v0
	v_mov_b32_e32 v69, v0
	v_mov_b32_e32 v24, v0
	v_mov_b32_e32 v25, v0
	v_mov_b32_e32 v26, v0
	v_mov_b32_e32 v27, v0
	v_mov_b32_e32 v90, v0
	v_mov_b32_e32 v91, v0
	v_mov_b32_e32 v92, v0
	v_mov_b32_e32 v93, v0
	v_mov_b32_e32 v4, v0
	v_mov_b32_e32 v5, v0
	v_mov_b32_e32 v6, v0
	v_mov_b32_e32 v7, v0
	v_mov_b32_e32 v28, v0
	v_mov_b32_e32 v29, v0
	v_mov_b32_e32 v30, v0
	v_mov_b32_e32 v31, v0
	v_mov_b32_e32 v32, v0
	v_mov_b32_e32 v33, v0
	v_mov_b32_e32 v34, v0
	v_mov_b32_e32 v35, v0
	v_mov_b32_e32 v98, v0
	v_mov_b32_e32 v99, v0
	v_mov_b32_e32 v100, v0
	v_mov_b32_e32 v101, v0
	v_mov_b32_e32 v58, v0
	v_mov_b32_e32 v59, v0
	v_mov_b32_e32 v60, v0
	v_mov_b32_e32 v61, v0
	v_mov_b32_e32 v122, v0
	v_mov_b32_e32 v123, v0
	v_mov_b32_e32 v124, v0
	v_mov_b32_e32 v125, v0
	v_mov_b32_e32 v62, v0
	v_mov_b32_e32 v63, v0
	v_mov_b32_e32 v64, v0
	v_mov_b32_e32 v65, v0
	v_mov_b32_e32 v36, v0
	v_mov_b32_e32 v37, v0
	v_mov_b32_e32 v38, v0
	v_mov_b32_e32 v39, v0
	v_mov_b32_e32 v94, v0
	v_mov_b32_e32 v95, v0
	v_mov_b32_e32 v96, v0
	v_mov_b32_e32 v97, v0
	v_mov_b32_e32 v70, v0
	v_mov_b32_e32 v71, v0
	v_mov_b32_e32 v72, v0
	v_mov_b32_e32 v73, v0
	v_mov_b32_e32 v8, v0
	v_mov_b32_e32 v9, v0
	v_mov_b32_e32 v10, v0
	v_mov_b32_e32 v11, v0
	v_mov_b32_e32 v74, v0
	v_mov_b32_e32 v75, v0
	v_mov_b32_e32 v76, v0
	v_mov_b32_e32 v77, v0
	v_mov_b32_e32 v16, v0
	v_mov_b32_e32 v17, v0
	v_mov_b32_e32 v18, v0
	v_mov_b32_e32 v19, v0
	v_mov_b32_e32 v82, v0
	v_mov_b32_e32 v83, v0
	v_mov_b32_e32 v84, v0
	v_mov_b32_e32 v85, v0
	v_mov_b32_e32 v12, v0
	v_mov_b32_e32 v13, v0
	v_mov_b32_e32 v14, v0
	v_mov_b32_e32 v15, v0
	v_mov_b32_e32 v78, v0
	v_mov_b32_e32 v79, v0
	v_mov_b32_e32 v80, v0
	v_mov_b32_e32 v81, v0
	v_mov_b32_e32 v20, v0
	v_mov_b32_e32 v21, v0
	v_mov_b32_e32 v22, v0
	v_mov_b32_e32 v23, v0
	v_mov_b32_e32 v86, v0
	v_mov_b32_e32 v87, v0
	v_mov_b32_e32 v88, v0
	v_mov_b32_e32 v89, v0
	v_mov_b32_e32 v40, v0
	v_mov_b32_e32 v41, v0
	v_mov_b32_e32 v42, v0
	v_mov_b32_e32 v43, v0
	v_mov_b32_e32 v106, v0
	v_mov_b32_e32 v107, v0
	v_mov_b32_e32 v108, v0
	v_mov_b32_e32 v109, v0
	v_mov_b32_e32 v50, v0
	v_mov_b32_e32 v51, v0
	v_mov_b32_e32 v52, v0
	v_mov_b32_e32 v53, v0
	v_mov_b32_e32 v114, v0
	v_mov_b32_e32 v115, v0
	v_mov_b32_e32 v116, v0
	v_mov_b32_e32 v117, v0
	v_mov_b32_e32 v102, v0
	v_mov_b32_e32 v103, v0
	v_mov_b32_e32 v104, v0
	v_mov_b32_e32 v105, v0
	v_mov_b32_e32 v44, v0
	v_mov_b32_e32 v45, v0
	v_mov_b32_e32 v46, v0
	v_mov_b32_e32 v47, v0
	v_mov_b32_e32 v110, v0
	v_mov_b32_e32 v111, v0
	v_mov_b32_e32 v112, v0
	v_mov_b32_e32 v113, v0
	v_mov_b32_e32 v54, v0
	v_mov_b32_e32 v55, v0
	v_mov_b32_e32 v56, v0
	v_mov_b32_e32 v57, v0
	v_mov_b32_e32 v118, v0
	v_mov_b32_e32 v119, v0
	v_mov_b32_e32 v120, v0
	v_mov_b32_e32 v121, v0
	v_mov_b32_e32 v126, v0
	v_mov_b32_e32 v127, v0
	v_mov_b32_e32 v128, v0
	v_mov_b32_e32 v129, v0
